# v13: rwkv_gn elementwise loop: gnw/gnb loads hoisted out of loop, next-row loads prefetched one iteration ahead
# baseline (speedup 1.0000x reference)
; __device__ __forceinline__ void rwkv_gn(bf16* OFb, const bf16* OBb, const bf16* Vb, const float* beta, const float* gnw, const float* gnb, int tid) {
;     const int lane = tid & 63, wave = tid >> 6; const int gw = blockIdx.x * 8 + wave, NGW = gridDim.x * 8;
;     for (int r = gw; r < SLAB; r += NGW) {
;         const size_t off = (size_t)r * 1024 + 16 * lane; const int head = lane >> 2;
;         float y[16], v[16]; float sm = 0.f;
; #pragma unroll
;         for (int h = 0; h < 2; ++h) { const u32x4_t a = *(const u32x4_t*)(OFb + off + 8 * h), b = *(const u32x4_t*)(OBb + off + 8 * h), vv = *(const u32x4_t*)(Vb + off + 8 * h);
;             const unsigned aw[4] = {a.x, a.y, a.z, a.w}, bw[4] = {b.x, b.y, b.z, b.w}, vw[4] = {vv.x, vv.y, vv.z, vv.w};
; #pragma unroll
;             for (int q = 0; q < 4; ++q) { y[8 * h + 2 * q] = __uint_as_float(aw[q] << 16) + __uint_as_float(bw[q] << 16); y[8 * h + 2 * q + 1] = __uint_as_float(aw[q] & 0xffff0000u) + __uint_as_float(bw[q] & 0xffff0000u);
;                 v[8 * h + 2 * q] = __uint_as_float(vw[q] << 16); v[8 * h + 2 * q + 1] = __uint_as_float(vw[q] & 0xffff0000u); } }
; #pragma unroll
;         for (int i = 0; i < 16; ++i) sm += y[i];
;         sm += __shfl_xor(sm, 1); sm += __shfl_xor(sm, 2);
;         const float mean = sm * (1.0f / 64.0f); float sv = 0.f;
.LBB0_117:
	s_andn2_b64 vcc, exec, s[0:1]
	s_cbranch_vccnz .LBB0_122
	v_ashrrev_i32_e32 v0, 6, v202
	v_add_u32_e32 v18, s93, v0
	s_movk_i32 s0, 0x4100
	v_cmp_gt_i32_e32 vcc, s0, v18
	s_and_saveexec_b64 s[0:1], vcc
	v_readlane_b32 s12, v254, 40
	v_readlane_b32 s18, v254, 42
	v_readlane_b32 s13, v254, 41
	v_readlane_b32 s19, v254, 43
	s_mov_b64 s[20:21], 0x7980000
	s_cbranch_execz .LBB0_121
	v_and_b32_e32 v3, 64, v198
	v_readlane_b32 s22, v255, 5
	v_xor_b32_e32 v0, 1, v198
	v_add_u32_e32 v3, 64, v3
	v_readlane_b32 s23, v255, 6
	v_cmp_lt_i32_e32 vcc, v0, v3
	s_load_dwordx4 s[8:11], s[22:23], 0xd0
	v_and_b32_e32 v2, 63, v203
	v_cndmask_b32_e32 v0, v198, v0, vcc
	s_waitcnt vmcnt(0)
	v_lshlrev_b32_e32 v40, 2, v0
	v_xor_b32_e32 v0, 2, v198
	v_cmp_lt_i32_e32 vcc, v0, v3
	v_ashrrev_i32_e32 v19, 31, v18
	v_lshlrev_b64 v[24:25], 6, v[18:19]
	v_cndmask_b32_e32 v0, v198, v0, vcc
	v_lshlrev_b32_e32 v41, 2, v0
	v_lshlrev_b32_e32 v0, 6, v2
	v_lshlrev_b64 v[26:27], 11, v[18:19]
	s_waitcnt lgkmcnt(0)
	v_lshl_add_u64 v[20:21], s[8:9], 0, v[0:1]
	v_lshl_add_u64 v[22:23], s[10:11], 0, v[0:1]
	v_and_or_b32 v24, v203, 60, v24
	v_lshl_or_b32 v26, v2, 5, v26
	s_mov_b64 s[8:9], 0
	global_load_dwordx4 v[100:103], v[20:21], off
	global_load_dwordx4 v[104:107], v[20:21], off offset:16
	global_load_dwordx4 v[108:111], v[20:21], off offset:32
	global_load_dwordx4 v[112:115], v[20:21], off offset:48
	global_load_dwordx4 v[116:119], v[22:23], off
	global_load_dwordx4 v[120:123], v[22:23], off offset:16
	global_load_dwordx4 v[124:127], v[22:23], off offset:32
	global_load_dwordx4 v[128:131], v[22:23], off offset:48
	v_lshl_add_u64 v[160:161], s[6:7], 0, v[26:27]
	v_lshl_add_u64 v[168:169], s[6:7], 0, v[24:25]
	v_add_co_u32_e32 v174, vcc, 0x5900000, v160
	s_nop 1
	v_addc_co_u32_e32 v175, vcc, 0, v161, vcc
	global_load_dwordx4 v[132:135], v[174:175], off
	global_load_dwordx4 v[136:139], v[174:175], off offset:16
	v_add_co_u32_e32 v164, vcc, 0x7980000, v160
	s_nop 1
	v_addc_co_u32_e32 v165, vcc, 0, v161, vcc
	global_load_dwordx4 v[140:143], v[164:165], off
	global_load_dwordx4 v[144:147], v[164:165], off offset:16
	v_add_co_u32_e32 v166, vcc, 0xdb00000, v160
	s_nop 1
	v_addc_co_u32_e32 v167, vcc, 0, v161, vcc
	global_load_dwordx4 v[148:151], v[166:167], off
	global_load_dwordx4 v[152:155], v[166:167], off offset:16
	v_add_co_u32_e32 v170, vcc, 0x100000, v168
	s_nop 1
	v_addc_co_u32_e32 v171, vcc, 0, v169, vcc
	global_load_dword v156, v[170:171], off
	v_add_co_u32_e32 v172, vcc, 0x204000, v168
	s_nop 1
	v_addc_co_u32_e32 v173, vcc, 0, v169, vcc
	global_load_dword v157, v[172:173], off
	s_waitcnt vmcnt(0)
.LBB0_120:
	s_waitcnt vmcnt(2)
	v_mov_b32_e32 v6, v132
	v_mov_b32_e32 v7, v133
	v_mov_b32_e32 v8, v134
	v_mov_b32_e32 v9, v135
	v_mov_b32_e32 v34, v136
	v_mov_b32_e32 v35, v137
	v_mov_b32_e32 v36, v138
	v_mov_b32_e32 v37, v139
	v_mov_b32_e32 v10, v140
	v_mov_b32_e32 v11, v141
	v_mov_b32_e32 v12, v142
	v_mov_b32_e32 v13, v143
	v_mov_b32_e32 v42, v144
	v_mov_b32_e32 v43, v145
	v_mov_b32_e32 v44, v146
	v_mov_b32_e32 v45, v147
	v_mov_b32_e32 v14, v148
	v_mov_b32_e32 v15, v149
	v_mov_b32_e32 v16, v150
	v_mov_b32_e32 v17, v151
	v_mov_b32_e32 v2, v152
	v_mov_b32_e32 v3, v153
	v_mov_b32_e32 v4, v154
	v_mov_b32_e32 v5, v155
	v_mov_b32_e32 v0, v156
	v_mov_b32_e32 v19, v157
	v_mov_b32_e32 v158, v174
	v_mov_b32_e32 v159, v175
	v_add_u32_e32 v18, s80, v18
	v_lshl_add_u64 v[26:27], v[26:27], 0, s[18:19]
	v_lshl_add_u64 v[24:25], v[24:25], 0, s[12:13]
	v_cmp_ge_i32_e32 vcc, s82, v18
	s_and_saveexec_b64 s[10:11], vcc
	v_lshl_add_u64 v[160:161], s[6:7], 0, v[26:27]
	v_lshl_add_u64 v[168:169], s[6:7], 0, v[24:25]
	v_add_co_u32_e32 v174, vcc, 0x5900000, v160
	s_nop 1
	v_addc_co_u32_e32 v175, vcc, 0, v161, vcc
	global_load_dwordx4 v[132:135], v[174:175], off
	global_load_dwordx4 v[136:139], v[174:175], off offset:16
	v_add_co_u32_e32 v164, vcc, 0x7980000, v160
	s_nop 1
	v_addc_co_u32_e32 v165, vcc, 0, v161, vcc
	global_load_dwordx4 v[140:143], v[164:165], off
	global_load_dwordx4 v[144:147], v[164:165], off offset:16
	v_add_co_u32_e32 v166, vcc, 0xdb00000, v160
	s_nop 1
	v_addc_co_u32_e32 v167, vcc, 0, v161, vcc
	global_load_dwordx4 v[148:151], v[166:167], off
	global_load_dwordx4 v[152:155], v[166:167], off offset:16
	v_add_co_u32_e32 v170, vcc, 0x100000, v168
	s_nop 1
	v_addc_co_u32_e32 v171, vcc, 0, v169, vcc
	global_load_dword v156, v[170:171], off
	v_add_co_u32_e32 v172, vcc, 0x204000, v168
	s_nop 1
	v_addc_co_u32_e32 v173, vcc, 0, v169, vcc
	global_load_dword v157, v[172:173], off
	s_mov_b64 exec, s[10:11]
	v_lshlrev_b32_e32 v78, 16, v6
	v_and_b32_e32 v30, 0xffff0000, v34
	v_lshlrev_b32_e32 v31, 16, v34
	v_and_b32_e32 v79, 0xffff0000, v6
	v_lshlrev_b32_e32 v6, 16, v10
	v_and_b32_e32 v32, 0xffff0000, v42
	v_lshlrev_b32_e32 v33, 16, v42
	v_pk_add_f32 v[30:31], v[30:31], v[32:33]
	v_and_b32_e32 v32, 0xffff0000, v35
	v_lshlrev_b32_e32 v33, 16, v35
	v_and_b32_e32 v34, 0xffff0000, v43
	v_lshlrev_b32_e32 v35, 16, v43
	v_pk_add_f32 v[32:33], v[32:33], v[34:35]
	v_and_b32_e32 v34, 0xffff0000, v36
	v_lshlrev_b32_e32 v35, 16, v36
	v_and_b32_e32 v38, 0xffff0000, v44
	v_lshlrev_b32_e32 v39, 16, v44
	v_pk_add_f32 v[34:35], v[34:35], v[38:39]
	v_and_b32_e32 v36, 0xffff0000, v37
	v_lshlrev_b32_e32 v37, 16, v37
	v_and_b32_e32 v38, 0xffff0000, v45
	v_lshlrev_b32_e32 v39, 16, v45
	v_pk_add_f32 v[36:37], v[36:37], v[38:39]
	s_nop 0
	s_nop 0
	v_lshlrev_b32_e32 v38, 16, v9
	v_and_b32_e32 v39, 0xffff0000, v9
	v_lshlrev_b32_e32 v42, 16, v13
	v_and_b32_e32 v43, 0xffff0000, v13
	v_pk_add_f32 v[74:75], v[38:39], v[42:43]
	v_lshlrev_b32_e32 v42, 16, v8
	v_and_b32_e32 v43, 0xffff0000, v8
	v_lshlrev_b32_e32 v8, 16, v12
	v_and_b32_e32 v9, 0xffff0000, v12
	v_pk_add_f32 v[12:13], v[42:43], v[8:9]
	v_lshlrev_b32_e32 v38, 16, v17
	v_and_b32_e32 v39, 0xffff0000, v17
	v_lshlrev_b32_e32 v8, 16, v16
	v_and_b32_e32 v9, 0xffff0000, v16
	v_lshlrev_b32_e32 v16, 16, v7
	v_and_b32_e32 v17, 0xffff0000, v7
	v_and_b32_e32 v7, 0xffff0000, v10
	v_pk_add_f32 v[6:7], v[78:79], v[6:7]
	v_lshlrev_b32_e32 v76, 16, v11
	v_and_b32_e32 v77, 0xffff0000, v11
	v_lshlrev_b32_e32 v10, 16, v14
	v_and_b32_e32 v11, 0xffff0000, v14
	v_add_f32_e32 v14, 0, v6
	v_pk_add_f32 v[16:17], v[16:17], v[76:77]
	v_add_f32_e32 v14, v7, v14
	v_add_f32_e32 v14, v16, v14
	v_add_f32_e32 v14, v17, v14
	v_add_f32_e32 v14, v12, v14
	v_add_f32_e32 v14, v13, v14
	v_add_f32_e32 v14, v74, v14
	v_add_f32_e32 v14, v75, v14
	v_add_f32_e32 v14, v31, v14
	v_add_f32_e32 v14, v30, v14
	v_add_f32_e32 v14, v33, v14
	v_add_f32_e32 v14, v32, v14
	v_add_f32_e32 v14, v35, v14
	v_add_f32_e32 v14, v34, v14
	v_add_f32_e32 v14, v37, v14
	v_add_f32_e32 v14, v36, v14
	v_lshlrev_b32_e32 v76, 16, v15
	v_and_b32_e32 v77, 0xffff0000, v15
	ds_bpermute_b32 v15, v40, v14
	v_lshlrev_b32_e32 v90, 16, v3
	v_and_b32_e32 v91, 0xffff0000, v3
	v_lshlrev_b32_e32 v94, 16, v2
	v_and_b32_e32 v95, 0xffff0000, v2
	s_waitcnt lgkmcnt(0)
; __device__ __forceinline__ unsigned pk2(float lo, float hi) { const f32x2_cv v = {lo, hi}; const bf16x2_cv b = __builtin_convertvector(v, bf16x2_cv); return __builtin_bit_cast(unsigned, b); }
; __device__ __forceinline__ void rwkv_gn(bf16* OFb, const bf16* OBb, const bf16* Vb, const float* beta, const float* gnw, const float* gnb, int tid) {
;     ...
;         sm += __shfl_xor(sm, 1); sm += __shfl_xor(sm, 2);
;         const float mean = sm * (1.0f / 64.0f); float sv = 0.f;
; #pragma unroll
;         for (int i = 0; i < 16; ++i) { const float dd = y[i] - mean; sv += dd * dd; }
;         sv += __shfl_xor(sv, 1); sv += __shfl_xor(sv, 2);
;         const float rs = rsqrtf(sv * (1.0f / 64.0f) + 64e-5f);
;         const float bt = beta[(size_t)r * 16 + head] + beta[((size_t)SLAB + r) * 16 + head];
;         float res[16];
; #pragma unroll
;         for (int i = 0; i < 16; ++i) res[i] = (y[i] - mean) * rs * gnw[16 * lane + i] + gnb[16 * lane + i] + bt * v[i];
; #pragma unroll
;         for (int h = 0; h < 2; ++h) { u32x4_t w; w.x = pk2(res[8 * h], res[8 * h + 1]); w.y = pk2(res[8 * h + 2], res[8 * h + 3]); w.z = pk2(res[8 * h + 4], res[8 * h + 5]); w.w = pk2(res[8 * h + 6], res[8 * h + 7]);
;             *(u32x4_t*)(OFb + off + 8 * h) = w; }
	v_add_f32_e32 v14, v14, v15
	ds_bpermute_b32 v15, v41, v14
	s_waitcnt lgkmcnt(0)
	v_add_f32_e32 v14, v14, v15
	v_mul_f32_e32 v14, 0x3c800000, v14
	v_pk_add_f32 v[6:7], v[6:7], v[14:15] op_sel_hi:[1,0] neg_lo:[0,1] neg_hi:[0,1]
	v_pk_add_f32 v[16:17], v[16:17], v[14:15] op_sel_hi:[1,0] neg_lo:[0,1] neg_hi:[0,1]
	v_pk_mul_f32 v[78:79], v[6:7], v[6:7]
	v_pk_mul_f32 v[80:81], v[16:17], v[16:17]
	v_pk_add_f32 v[12:13], v[12:13], v[14:15] op_sel_hi:[1,0] neg_lo:[0,1] neg_hi:[0,1]
	v_pk_add_f32 v[74:75], v[74:75], v[14:15] op_sel_hi:[1,0] neg_lo:[0,1] neg_hi:[0,1]
	v_pk_mul_f32 v[82:83], v[12:13], v[12:13]
	v_pk_mul_f32 v[84:85], v[74:75], v[74:75]
	v_pk_add_f32 v[2:3], v[30:31], v[14:15] op_sel_hi:[1,0] neg_lo:[0,1] neg_hi:[0,1]
	v_pk_add_f32 v[34:35], v[34:35], v[14:15] op_sel_hi:[1,0] neg_lo:[0,1] neg_hi:[0,1]
	v_pk_add_f32 v[36:37], v[36:37], v[14:15] op_sel_hi:[1,0] neg_lo:[0,1] neg_hi:[0,1]
	v_pk_add_f32 v[32:33], v[32:33], v[14:15] op_sel_hi:[1,0] neg_lo:[0,1] neg_hi:[0,1]
	v_pk_mul_f32 v[14:15], v[2:3], v[2:3]
	v_pk_mul_f32 v[92:93], v[32:33], v[32:33]
	v_pk_mul_f32 v[86:87], v[34:35], v[34:35]
	v_pk_mul_f32 v[88:89], v[36:37], v[36:37]
	v_add_f32_e32 v0, v0, v19
	v_add_f32_e32 v19, v78, v79
	v_add_f32_e32 v19, v80, v19
	v_add_f32_e32 v19, v81, v19
	v_add_f32_e32 v19, v82, v19
	v_add_f32_e32 v19, v83, v19
	v_add_f32_e32 v19, v84, v19
	v_add_f32_e32 v19, v85, v19
	v_add_f32_e32 v15, v15, v19
	v_add_f32_e32 v14, v14, v15
	v_add_f32_e32 v14, v93, v14
	v_add_f32_e32 v14, v92, v14
	v_add_f32_e32 v14, v87, v14
	v_add_f32_e32 v14, v86, v14
	v_add_f32_e32 v14, v89, v14
	v_add_f32_e32 v14, v88, v14
	ds_bpermute_b32 v15, v40, v14
	s_waitcnt lgkmcnt(0)
	v_add_f32_e32 v14, v14, v15
	ds_bpermute_b32 v15, v41, v14
	s_waitcnt lgkmcnt(0)
	v_add_f32_e32 v14, v14, v15
	v_mov_b32_e32 v15, 0x3a27c5ac
	v_fmamk_f32 v14, v14, 0x3c800000, v15
	v_cmp_gt_f32_e32 vcc, s33, v14
	v_mul_f32_e32 v15, 0x4b800000, v14
	s_nop 0
	v_cndmask_b32_e32 v14, v14, v15, vcc
	v_rsq_f32_e32 v14, v14
	s_nop 0
	v_mul_f32_e32 v15, 0x45800000, v14
	v_cndmask_b32_e32 v14, v14, v15, vcc
	v_pk_mul_f32 v[6:7], v[6:7], v[14:15] op_sel_hi:[1,0]
	v_pk_mul_f32 v[2:3], v[2:3], v[14:15] op_sel_hi:[1,0]
	v_pk_fma_f32 v[6:7], v[100:101], v[6:7], v[116:117]
	v_pk_fma_f32 v[2:3], v[108:109], v[2:3], v[124:125] op_sel:[0,1,0] op_sel_hi:[1,0,1]
	v_pk_fma_f32 v[6:7], v[0:1], v[10:11], v[6:7] op_sel_hi:[0,1,1]
	v_pk_mul_f32 v[10:11], v[16:17], v[14:15] op_sel_hi:[1,0]
	v_pk_mul_f32 v[12:13], v[12:13], v[14:15] op_sel_hi:[1,0]
	v_pk_fma_f32 v[16:17], v[0:1], v[94:95], v[2:3] op_sel_hi:[0,1,1]
	v_pk_mul_f32 v[2:3], v[32:33], v[14:15] op_sel_hi:[1,0]
	v_pk_fma_f32 v[12:13], v[104:105], v[12:13], v[120:121]
	v_pk_fma_f32 v[2:3], v[110:111], v[2:3], v[126:127] op_sel:[0,1,0] op_sel_hi:[1,0,1]
	v_pk_mul_f32 v[32:33], v[34:35], v[14:15] op_sel_hi:[1,0]
	v_pk_fma_f32 v[8:9], v[0:1], v[8:9], v[12:13] op_sel_hi:[0,1,1]
	v_pk_mul_f32 v[12:13], v[74:75], v[14:15] op_sel_hi:[1,0]
	v_pk_fma_f32 v[30:31], v[0:1], v[90:91], v[2:3] op_sel_hi:[0,1,1]
	v_lshlrev_b32_e32 v2, 16, v4
	v_and_b32_e32 v3, 0xffff0000, v4
	v_pk_fma_f32 v[32:33], v[112:113], v[32:33], v[128:129] op_sel:[0,1,0] op_sel_hi:[1,0,1]
	v_pk_fma_f32 v[10:11], v[102:103], v[10:11], v[118:119]
	v_pk_fma_f32 v[12:13], v[106:107], v[12:13], v[122:123]
	v_pk_fma_f32 v[32:33], v[0:1], v[2:3], v[32:33] op_sel_hi:[0,1,1]
	v_lshlrev_b32_e32 v2, 16, v5
	v_and_b32_e32 v3, 0xffff0000, v5
	v_pk_mul_f32 v[4:5], v[36:37], v[14:15] op_sel_hi:[1,0]
	v_pk_fma_f32 v[10:11], v[0:1], v[76:77], v[10:11] op_sel_hi:[0,1,1]
	v_pk_fma_f32 v[12:13], v[0:1], v[38:39], v[12:13] op_sel_hi:[0,1,1]
	v_pk_fma_f32 v[4:5], v[114:115], v[4:5], v[130:131] op_sel:[0,1,0] op_sel_hi:[1,0,1]
	v_cmp_lt_i32_e32 vcc, s82, v18
	v_pk_fma_f32 v[14:15], v[0:1], v[2:3], v[4:5] op_sel_hi:[0,1,1]
	v_cvt_pk_bf16_f32 v2, v6, v7
	v_cvt_pk_bf16_f32 v3, v10, v11
	v_cvt_pk_bf16_f32 v4, v8, v9
	v_cvt_pk_bf16_f32 v5, v12, v13
	global_store_dwordx4 v[158:159], v[2:5], off
	s_or_b64 s[8:9], vcc, s[8:9]
	s_nop 0
	v_cvt_pk_bf16_f32 v2, v16, v17
	v_cvt_pk_bf16_f32 v3, v30, v31
	v_cvt_pk_bf16_f32 v4, v32, v33
	v_cvt_pk_bf16_f32 v5, v14, v15
	global_store_dwordx4 v[158:159], v[2:5], off offset:16
	s_andn2_b64 exec, exec, s[8:9]
	s_cbranch_execnz .LBB0_120
